# P7 rope-part epilogue table loads software-pipelined by one group (no store merging), for comparison with the merged-store build
# speedup vs baseline: 1.0988x; 1.0195x over previous
.LBB0_1143:
	s_andn2_b64 vcc, exec, s[0:1]
	s_cbranch_vccnz .LBB0_1002
	v_lshl_add_u32 v154, s40, 8, v162
	v_and_b32_e32 v132, 0xfcf, v154
	v_cmp_gt_i32_e32 vcc, s49, v154
	s_cmp_lt_i32 s38, 4
	s_cselect_b64 s[0:1], -1, 0
	v_cndmask_b32_e32 v132, v164, v132, vcc
	v_lshlrev_b32_e32 v132, 10, v132
	v_lshl_add_u64 v[152:153], v[138:139], 0, v[132:133]
	global_load_dwordx4 v[156:159], v[152:153], off
	global_load_dwordx4 v[170:173], v[152:153], off offset:16
	v_cndmask_b32_e64 v151, v168, 1.0, s[0:1]
	s_and_b64 s[0:1], s[0:1], exec
	s_cselect_b32 s1, s31, s35
	s_cselect_b32 s0, s30, s34
	s_lshl_b32 s8, s38, 9
	v_mov_b32_e32 v160, v124
	v_mov_b32_e32 v161, v120
	v_mov_b32_e32 v174, v120
	v_mov_b32_e32 v175, v124
	v_mov_b32_e32 v120, v125
	v_mov_b32_e32 v124, v121
	v_mov_b32_e32 v176, v126
	v_mov_b32_e32 v177, v122
	s_and_b32 s8, s8, 0x600
	v_mov_b32_e32 v178, v122
	v_mov_b32_e32 v179, v126
	v_mov_b32_e32 v122, v127
	v_mov_b32_e32 v126, v123
	v_ashrrev_i32_e32 v155, 31, v154
	s_add_u32 s0, s0, s8
	v_lshlrev_b64 v[180:181], 11, v[154:155]
	v_lshl_add_u64 v[182:183], v[140:141], 0, v[132:133]
	s_addc_u32 s1, s1, 0
	v_lshlrev_b32_e32 v152, 1, v134
	v_mov_b32_e32 v153, v133
	v_lshl_add_u64 v[180:181], s[0:1], 0, v[180:181]
	v_lshl_add_u64 v[180:181], v[180:181], 0, v[152:153]
	s_movk_i32 s8, 0xfdf
	s_waitcnt vmcnt(0)
	global_load_dwordx4 v[208:211], v[182:183], off
	global_load_dwordx4 v[212:215], v[182:183], off offset:16
	v_pk_mul_f32 v[160:161], v[160:161], v[156:157]
	v_pk_mul_f32 v[120:121], v[120:121], v[158:159]
	v_pk_mul_f32 v[124:125], v[124:125], v[158:159]
	v_pk_mul_f32 v[158:159], v[176:177], v[170:171]
	v_pk_mul_f32 v[122:123], v[122:123], v[172:173]
	v_pk_mul_f32 v[126:127], v[126:127], v[172:173]
	v_sub_f32_e32 v132, v160, v161
	v_sub_f32_e32 v120, v120, v121
	v_add_f32_e32 v121, v125, v124
	v_sub_f32_e32 v124, v158, v159
	v_pk_mul_f32 v[156:157], v[174:175], v[156:157]
	v_pk_mul_f32 v[170:171], v[178:179], v[170:171]
	v_sub_f32_e32 v122, v122, v123
	v_add_f32_e32 v123, v127, v126
	v_mul_f32_e32 v126, v151, v132
	v_mul_f32_e32 v120, v151, v120
	v_mul_f32_e32 v132, v151, v121
	v_mul_f32_e32 v121, v151, v124
	v_add_f32_e32 v155, v157, v156
	v_add_f32_e32 v125, v171, v170
	v_mul_f32_e32 v122, v151, v122
	v_cvt_pk_bf16_f32 v120, v126, v120
	v_cvt_pk_bf16_f32 v121, v121, v122
	v_mul_f32_e32 v127, v151, v155
	v_mul_f32_e32 v124, v151, v125
	v_mul_f32_e32 v123, v151, v123
	global_store_dwordx2 v[180:181], v[120:121], off
	v_cvt_pk_bf16_f32 v120, v127, v132
	v_cvt_pk_bf16_f32 v121, v124, v123
	global_store_dwordx2 v[180:181], v[120:121], off offset:256
	v_mov_b32_e32 v156, v116
	v_mov_b32_e32 v157, v112
	v_mov_b32_e32 v158, v112
	v_mov_b32_e32 v159, v116
	v_mov_b32_e32 v112, v117
	v_mov_b32_e32 v116, v113
	v_mov_b32_e32 v160, v118
	v_mov_b32_e32 v161, v114
	v_mov_b32_e32 v170, v114
	v_mov_b32_e32 v171, v118
	v_mov_b32_e32 v114, v119
	v_mov_b32_e32 v118, v115
	v_or_b32_e32 v172, 16, v154
	v_bitop3_b32 v132, v154, s8, 16 bitop3:0xc8
	v_cmp_gt_i32_e32 vcc, s49, v172
	v_ashrrev_i32_e32 v173, 31, v172
	s_movk_i32 s8, 0xfef
	v_cndmask_b32_e32 v132, v164, v132, vcc
	v_lshlrev_b32_e32 v132, 10, v132
	v_lshl_add_u64 v[174:175], v[138:139], 0, v[132:133]
	s_waitcnt vmcnt(2)
	global_load_dwordx4 v[200:203], v[174:175], off
	global_load_dwordx4 v[204:207], v[174:175], off offset:16
	v_pk_mul_f32 v[156:157], v[156:157], v[208:209]
	v_pk_mul_f32 v[120:121], v[158:159], v[208:209]
	v_pk_mul_f32 v[112:113], v[112:113], v[210:211]
	v_pk_mul_f32 v[116:117], v[116:117], v[210:211]
	v_pk_mul_f32 v[122:123], v[160:161], v[212:213]
	v_pk_mul_f32 v[114:115], v[114:115], v[214:215]
	v_pk_mul_f32 v[118:119], v[118:119], v[214:215]
	v_add_f32_e32 v120, v121, v120
	v_sub_f32_e32 v112, v112, v113
	v_add_f32_e32 v113, v117, v116
	v_sub_f32_e32 v116, v122, v123
	v_pk_mul_f32 v[124:125], v[170:171], v[212:213]
	v_sub_f32_e32 v126, v156, v157
	v_sub_f32_e32 v114, v114, v115
	v_add_f32_e32 v115, v119, v118
	v_mul_f32_e32 v119, v151, v120
	v_mul_f32_e32 v112, v151, v112
	v_mul_f32_e32 v120, v151, v113
	v_mul_f32_e32 v113, v151, v116
	v_add_f32_e32 v117, v125, v124
	v_mul_f32_e32 v118, v151, v126
	v_mul_f32_e32 v114, v151, v114
	v_cvt_pk_bf16_f32 v112, v118, v112
	v_cvt_pk_bf16_f32 v113, v113, v114
	v_mul_f32_e32 v116, v151, v117
	v_mul_f32_e32 v115, v151, v115
	global_store_dwordx2 v[180:181], v[112:113], off offset:32
	v_cvt_pk_bf16_f32 v112, v119, v120
	v_cvt_pk_bf16_f32 v113, v116, v115
	global_store_dwordx2 v[180:181], v[112:113], off offset:288
	v_mov_b32_e32 v120, v108
	v_mov_b32_e32 v121, v104
	v_mov_b32_e32 v122, v104
	v_mov_b32_e32 v123, v108
	v_mov_b32_e32 v104, v109
	v_mov_b32_e32 v108, v105
	v_mov_b32_e32 v124, v110
	v_mov_b32_e32 v125, v106
	v_mov_b32_e32 v126, v106
	v_mov_b32_e32 v127, v110
	v_mov_b32_e32 v106, v111
	v_mov_b32_e32 v110, v107
	v_lshlrev_b64 v[156:157], 11, v[172:173]
	v_lshl_add_u64 v[156:157], s[0:1], 0, v[156:157]
	v_lshl_add_u64 v[156:157], v[156:157], 0, v[152:153]
	v_lshl_add_u64 v[158:159], v[140:141], 0, v[132:133]
	s_waitcnt vmcnt(2)
	global_load_dwordx4 v[208:211], v[158:159], off
	global_load_dwordx4 v[212:215], v[158:159], off offset:16
	v_pk_mul_f32 v[120:121], v[120:121], v[200:201]
	v_pk_mul_f32 v[112:113], v[122:123], v[200:201]
	v_pk_mul_f32 v[104:105], v[104:105], v[202:203]
	v_pk_mul_f32 v[108:109], v[108:109], v[202:203]
	v_pk_mul_f32 v[114:115], v[124:125], v[204:205]
	v_pk_mul_f32 v[106:107], v[106:107], v[206:207]
	v_pk_mul_f32 v[110:111], v[110:111], v[206:207]
	v_add_f32_e32 v112, v113, v112
	v_sub_f32_e32 v104, v104, v105
	v_add_f32_e32 v105, v109, v108
	v_sub_f32_e32 v108, v114, v115
	v_pk_mul_f32 v[116:117], v[126:127], v[204:205]
	v_sub_f32_e32 v118, v120, v121
	v_sub_f32_e32 v106, v106, v107
	v_add_f32_e32 v107, v111, v110
	v_mul_f32_e32 v111, v151, v112
	v_mul_f32_e32 v104, v151, v104
	v_mul_f32_e32 v112, v151, v105
	v_mul_f32_e32 v105, v151, v108
	v_add_f32_e32 v109, v117, v116
	v_mul_f32_e32 v110, v151, v118
	v_mul_f32_e32 v106, v151, v106
	v_cvt_pk_bf16_f32 v104, v110, v104
	v_cvt_pk_bf16_f32 v105, v105, v106
	v_mul_f32_e32 v108, v151, v109
	v_mul_f32_e32 v107, v151, v107
	global_store_dwordx2 v[156:157], v[104:105], off
	v_cvt_pk_bf16_f32 v104, v111, v112
	v_cvt_pk_bf16_f32 v105, v108, v107
	global_store_dwordx2 v[156:157], v[104:105], off offset:256
	v_mov_b32_e32 v112, v100
	v_mov_b32_e32 v113, v96
	v_mov_b32_e32 v114, v96
	v_mov_b32_e32 v115, v100
	v_mov_b32_e32 v96, v101
	v_mov_b32_e32 v100, v97
	v_mov_b32_e32 v116, v102
	v_mov_b32_e32 v117, v98
	v_mov_b32_e32 v118, v98
	v_mov_b32_e32 v119, v102
	v_mov_b32_e32 v98, v103
	v_mov_b32_e32 v102, v99
	v_or_b32_e32 v120, 32, v154
	v_bitop3_b32 v121, v154, s8, 32 bitop3:0xc8
	v_cmp_gt_i32_e32 vcc, s49, v120
	s_movk_i32 s8, 0xfff
	s_waitcnt vmcnt(2)
	v_pk_mul_f32 v[112:113], v[112:113], v[208:209]
	v_pk_mul_f32 v[104:105], v[114:115], v[208:209]
	v_pk_mul_f32 v[96:97], v[96:97], v[210:211]
	v_pk_mul_f32 v[100:101], v[100:101], v[210:211]
	v_pk_mul_f32 v[106:107], v[116:117], v[212:213]
	v_pk_mul_f32 v[98:99], v[98:99], v[214:215]
	v_pk_mul_f32 v[102:103], v[102:103], v[214:215]
	v_add_f32_e32 v104, v105, v104
	v_sub_f32_e32 v96, v96, v97
	v_add_f32_e32 v97, v101, v100
	v_sub_f32_e32 v100, v106, v107
	v_cndmask_b32_e32 v121, v164, v121, vcc
	v_pk_mul_f32 v[108:109], v[118:119], v[212:213]
	v_sub_f32_e32 v110, v112, v113
	v_sub_f32_e32 v98, v98, v99
	v_add_f32_e32 v99, v103, v102
	v_mul_f32_e32 v103, v151, v104
	v_mul_f32_e32 v96, v151, v96
	v_mul_f32_e32 v104, v151, v97
	v_mul_f32_e32 v97, v151, v100
	v_lshlrev_b32_e32 v132, 10, v121
	v_add_f32_e32 v101, v109, v108
	v_mul_f32_e32 v102, v151, v110
	v_mul_f32_e32 v98, v151, v98
	v_cvt_pk_bf16_f32 v96, v102, v96
	v_cvt_pk_bf16_f32 v97, v97, v98
	v_lshl_add_u64 v[122:123], v[138:139], 0, v[132:133]
	global_load_dwordx4 v[200:203], v[122:123], off
	global_load_dwordx4 v[204:207], v[122:123], off offset:16
	v_mul_f32_e32 v100, v151, v101
	v_mul_f32_e32 v99, v151, v99
	global_store_dwordx2 v[156:157], v[96:97], off offset:32
	v_cvt_pk_bf16_f32 v96, v103, v104
	v_cvt_pk_bf16_f32 v97, v100, v99
	global_store_dwordx2 v[156:157], v[96:97], off offset:288
	v_mov_b32_e32 v104, v92
	v_mov_b32_e32 v105, v88
	v_mov_b32_e32 v106, v88
	v_mov_b32_e32 v107, v92
	v_mov_b32_e32 v88, v93
	v_mov_b32_e32 v92, v89
	v_mov_b32_e32 v108, v94
	v_mov_b32_e32 v109, v90
	v_mov_b32_e32 v110, v90
	v_mov_b32_e32 v111, v94
	v_mov_b32_e32 v90, v95
	v_mov_b32_e32 v94, v91
	v_ashrrev_i32_e32 v121, 31, v120
	v_lshlrev_b64 v[112:113], 11, v[120:121]
	v_lshl_add_u64 v[112:113], s[0:1], 0, v[112:113]
	v_lshl_add_u64 v[112:113], v[112:113], 0, v[152:153]
	v_lshl_add_u64 v[114:115], v[140:141], 0, v[132:133]
	s_waitcnt vmcnt(2)
	global_load_dwordx4 v[208:211], v[114:115], off
	global_load_dwordx4 v[212:215], v[114:115], off offset:16
	v_pk_mul_f32 v[104:105], v[104:105], v[200:201]
	v_pk_mul_f32 v[96:97], v[106:107], v[200:201]
	v_pk_mul_f32 v[88:89], v[88:89], v[202:203]
	v_pk_mul_f32 v[92:93], v[92:93], v[202:203]
	v_pk_mul_f32 v[98:99], v[108:109], v[204:205]
	v_pk_mul_f32 v[90:91], v[90:91], v[206:207]
	v_pk_mul_f32 v[94:95], v[94:95], v[206:207]
	v_add_f32_e32 v96, v97, v96
	v_sub_f32_e32 v88, v88, v89
	v_add_f32_e32 v89, v93, v92
	v_sub_f32_e32 v92, v98, v99
	v_pk_mul_f32 v[100:101], v[110:111], v[204:205]
	v_sub_f32_e32 v102, v104, v105
	v_sub_f32_e32 v90, v90, v91
	v_add_f32_e32 v91, v95, v94
	v_mul_f32_e32 v95, v151, v96
	v_mul_f32_e32 v88, v151, v88
	v_mul_f32_e32 v96, v151, v89
	v_mul_f32_e32 v89, v151, v92
	v_add_f32_e32 v93, v101, v100
	v_mul_f32_e32 v94, v151, v102
	v_mul_f32_e32 v90, v151, v90
	v_cvt_pk_bf16_f32 v88, v94, v88
	v_cvt_pk_bf16_f32 v89, v89, v90
	v_mul_f32_e32 v92, v151, v93
	v_mul_f32_e32 v91, v151, v91
	global_store_dwordx2 v[112:113], v[88:89], off
	v_cvt_pk_bf16_f32 v88, v95, v96
	v_cvt_pk_bf16_f32 v89, v92, v91
	global_store_dwordx2 v[112:113], v[88:89], off offset:256
	v_mov_b32_e32 v96, v84
	v_mov_b32_e32 v97, v80
	v_mov_b32_e32 v98, v80
	v_mov_b32_e32 v99, v84
	v_mov_b32_e32 v80, v85
	v_mov_b32_e32 v84, v81
	v_mov_b32_e32 v100, v86
	v_mov_b32_e32 v101, v82
	v_mov_b32_e32 v102, v82
	v_mov_b32_e32 v103, v86
	v_mov_b32_e32 v82, v87
	v_mov_b32_e32 v86, v83
	v_or_b32_e32 v104, 48, v154
	v_bitop3_b32 v105, v154, s8, 48 bitop3:0xc8
	v_cmp_gt_i32_e32 vcc, s49, v104
	s_waitcnt vmcnt(2)
	v_pk_mul_f32 v[96:97], v[96:97], v[208:209]
	v_pk_mul_f32 v[88:89], v[98:99], v[208:209]
	v_pk_mul_f32 v[80:81], v[80:81], v[210:211]
	v_pk_mul_f32 v[84:85], v[84:85], v[210:211]
	v_pk_mul_f32 v[90:91], v[100:101], v[212:213]
	v_pk_mul_f32 v[82:83], v[82:83], v[214:215]
	v_pk_mul_f32 v[86:87], v[86:87], v[214:215]
	v_add_f32_e32 v88, v89, v88
	v_sub_f32_e32 v80, v80, v81
	v_add_f32_e32 v81, v85, v84
	v_sub_f32_e32 v84, v90, v91
	v_cndmask_b32_e32 v105, v164, v105, vcc
	v_pk_mul_f32 v[92:93], v[102:103], v[212:213]
	v_sub_f32_e32 v94, v96, v97
	v_sub_f32_e32 v82, v82, v83
	v_add_f32_e32 v83, v87, v86
	v_mul_f32_e32 v87, v151, v88
	v_mul_f32_e32 v80, v151, v80
	v_mul_f32_e32 v88, v151, v81
	v_mul_f32_e32 v81, v151, v84
	v_lshlrev_b32_e32 v132, 10, v105
	v_add_f32_e32 v85, v93, v92
	v_mul_f32_e32 v86, v151, v94
	v_mul_f32_e32 v82, v151, v82
	v_cvt_pk_bf16_f32 v80, v86, v80
	v_cvt_pk_bf16_f32 v81, v81, v82
	v_lshl_add_u64 v[106:107], v[138:139], 0, v[132:133]
	global_load_dwordx4 v[200:203], v[106:107], off
	global_load_dwordx4 v[204:207], v[106:107], off offset:16
	v_mul_f32_e32 v84, v151, v85
	v_mul_f32_e32 v83, v151, v83
	global_store_dwordx2 v[112:113], v[80:81], off offset:32
	v_cvt_pk_bf16_f32 v80, v87, v88
	v_cvt_pk_bf16_f32 v81, v84, v83
	global_store_dwordx2 v[112:113], v[80:81], off offset:288
	v_mov_b32_e32 v88, v76
	v_mov_b32_e32 v89, v72
	v_mov_b32_e32 v90, v72
	v_mov_b32_e32 v91, v76
	v_mov_b32_e32 v72, v77
	v_mov_b32_e32 v76, v73
	v_mov_b32_e32 v92, v78
	v_mov_b32_e32 v93, v74
	v_mov_b32_e32 v94, v74
	v_mov_b32_e32 v95, v78
	v_mov_b32_e32 v74, v79
	v_mov_b32_e32 v78, v75
	v_ashrrev_i32_e32 v105, 31, v104
	v_lshlrev_b64 v[96:97], 11, v[104:105]
	v_lshl_add_u64 v[96:97], s[0:1], 0, v[96:97]
	v_lshl_add_u64 v[96:97], v[96:97], 0, v[152:153]
	v_lshl_add_u64 v[98:99], v[140:141], 0, v[132:133]
	s_waitcnt vmcnt(2)
	global_load_dwordx4 v[208:211], v[98:99], off
	global_load_dwordx4 v[212:215], v[98:99], off offset:16
	v_pk_mul_f32 v[88:89], v[88:89], v[200:201]
	v_pk_mul_f32 v[80:81], v[90:91], v[200:201]
	v_pk_mul_f32 v[72:73], v[72:73], v[202:203]
	v_pk_mul_f32 v[76:77], v[76:77], v[202:203]
	v_pk_mul_f32 v[82:83], v[92:93], v[204:205]
	v_pk_mul_f32 v[74:75], v[74:75], v[206:207]
	v_pk_mul_f32 v[78:79], v[78:79], v[206:207]
	v_add_f32_e32 v80, v81, v80
	v_sub_f32_e32 v72, v72, v73
	v_add_f32_e32 v73, v77, v76
	v_sub_f32_e32 v76, v82, v83
	v_pk_mul_f32 v[84:85], v[94:95], v[204:205]
	v_sub_f32_e32 v86, v88, v89
	v_sub_f32_e32 v74, v74, v75
	v_add_f32_e32 v75, v79, v78
	v_mul_f32_e32 v79, v151, v80
	v_mul_f32_e32 v72, v151, v72
	v_mul_f32_e32 v80, v151, v73
	v_mul_f32_e32 v73, v151, v76
	v_add_f32_e32 v77, v85, v84
	v_mul_f32_e32 v78, v151, v86
	v_mul_f32_e32 v74, v151, v74
	v_cvt_pk_bf16_f32 v72, v78, v72
	v_cvt_pk_bf16_f32 v73, v73, v74
	v_mul_f32_e32 v76, v151, v77
	v_mul_f32_e32 v75, v151, v75
	global_store_dwordx2 v[96:97], v[72:73], off
	v_cvt_pk_bf16_f32 v72, v79, v80
	v_cvt_pk_bf16_f32 v73, v76, v75
	global_store_dwordx2 v[96:97], v[72:73], off offset:256
	v_mov_b32_e32 v80, v68
	v_mov_b32_e32 v81, v64
	v_mov_b32_e32 v82, v64
	v_mov_b32_e32 v83, v68
	v_mov_b32_e32 v64, v69
	v_mov_b32_e32 v68, v65
	v_mov_b32_e32 v84, v70
	v_mov_b32_e32 v85, v66
	v_mov_b32_e32 v86, v66
	v_mov_b32_e32 v87, v70
	v_mov_b32_e32 v66, v71
	v_mov_b32_e32 v70, v67
	v_add_u32_e32 v88, 0x80, v154
	v_and_b32_e32 v89, 0xfcf, v88
	v_cmp_gt_i32_e32 vcc, s49, v88
	s_waitcnt vmcnt(2)
	v_pk_mul_f32 v[80:81], v[80:81], v[208:209]
	v_pk_mul_f32 v[72:73], v[82:83], v[208:209]
	v_pk_mul_f32 v[64:65], v[64:65], v[210:211]
	v_pk_mul_f32 v[68:69], v[68:69], v[210:211]
	v_pk_mul_f32 v[74:75], v[84:85], v[212:213]
	v_pk_mul_f32 v[66:67], v[66:67], v[214:215]
	v_pk_mul_f32 v[70:71], v[70:71], v[214:215]
	v_add_f32_e32 v72, v73, v72
	v_sub_f32_e32 v64, v64, v65
	v_add_f32_e32 v65, v69, v68
	v_sub_f32_e32 v68, v74, v75
	v_cndmask_b32_e32 v89, v164, v89, vcc
	v_pk_mul_f32 v[76:77], v[86:87], v[212:213]
	v_sub_f32_e32 v78, v80, v81
	v_sub_f32_e32 v66, v66, v67
	v_add_f32_e32 v67, v71, v70
	v_mul_f32_e32 v71, v151, v72
	v_mul_f32_e32 v64, v151, v64
	v_mul_f32_e32 v72, v151, v65
	v_mul_f32_e32 v65, v151, v68
	v_lshlrev_b32_e32 v132, 10, v89
	v_add_f32_e32 v69, v77, v76
	v_mul_f32_e32 v70, v151, v78
	v_mul_f32_e32 v66, v151, v66
	v_cvt_pk_bf16_f32 v64, v70, v64
	v_cvt_pk_bf16_f32 v65, v65, v66
	v_lshl_add_u64 v[90:91], v[138:139], 0, v[132:133]
	global_load_dwordx4 v[200:203], v[90:91], off
	global_load_dwordx4 v[204:207], v[90:91], off offset:16
	v_mul_f32_e32 v68, v151, v69
	v_mul_f32_e32 v67, v151, v67
	global_store_dwordx2 v[96:97], v[64:65], off offset:32
	v_cvt_pk_bf16_f32 v64, v71, v72
	v_cvt_pk_bf16_f32 v65, v68, v67
	global_store_dwordx2 v[96:97], v[64:65], off offset:288
	v_mov_b32_e32 v72, v60
	v_mov_b32_e32 v73, v56
	v_mov_b32_e32 v74, v56
	v_mov_b32_e32 v75, v60
	v_mov_b32_e32 v56, v61
	v_mov_b32_e32 v60, v57
	v_mov_b32_e32 v76, v62
	v_mov_b32_e32 v77, v58
	v_mov_b32_e32 v78, v58
	v_mov_b32_e32 v79, v62
	v_mov_b32_e32 v58, v63
	v_mov_b32_e32 v62, v59
	v_ashrrev_i32_e32 v89, 31, v88
	v_lshlrev_b64 v[80:81], 11, v[88:89]
	v_lshl_add_u64 v[80:81], s[0:1], 0, v[80:81]
	v_lshl_add_u64 v[80:81], v[80:81], 0, v[152:153]
	v_lshl_add_u64 v[82:83], v[140:141], 0, v[132:133]
	s_waitcnt vmcnt(2)
	global_load_dwordx4 v[208:211], v[82:83], off
	global_load_dwordx4 v[212:215], v[82:83], off offset:16
	v_pk_mul_f32 v[72:73], v[72:73], v[200:201]
	v_pk_mul_f32 v[64:65], v[74:75], v[200:201]
	v_pk_mul_f32 v[56:57], v[56:57], v[202:203]
	v_pk_mul_f32 v[60:61], v[60:61], v[202:203]
	v_pk_mul_f32 v[66:67], v[76:77], v[204:205]
	v_pk_mul_f32 v[58:59], v[58:59], v[206:207]
	v_pk_mul_f32 v[62:63], v[62:63], v[206:207]
	v_add_f32_e32 v64, v65, v64
	v_sub_f32_e32 v56, v56, v57
	v_add_f32_e32 v57, v61, v60
	v_sub_f32_e32 v60, v66, v67
	v_pk_mul_f32 v[68:69], v[78:79], v[204:205]
	v_sub_f32_e32 v70, v72, v73
	v_sub_f32_e32 v58, v58, v59
	v_add_f32_e32 v59, v63, v62
	v_mul_f32_e32 v63, v151, v64
	v_mul_f32_e32 v56, v151, v56
	v_mul_f32_e32 v64, v151, v57
	v_mul_f32_e32 v57, v151, v60
	v_add_f32_e32 v61, v69, v68
	v_mul_f32_e32 v62, v151, v70
	v_mul_f32_e32 v58, v151, v58
	v_cvt_pk_bf16_f32 v56, v62, v56
	v_cvt_pk_bf16_f32 v57, v57, v58
	v_mul_f32_e32 v60, v151, v61
	v_mul_f32_e32 v59, v151, v59
	global_store_dwordx2 v[80:81], v[56:57], off
	v_cvt_pk_bf16_f32 v56, v63, v64
	v_cvt_pk_bf16_f32 v57, v60, v59
	global_store_dwordx2 v[80:81], v[56:57], off offset:256
	v_mov_b32_e32 v64, v52
	v_mov_b32_e32 v65, v48
	v_mov_b32_e32 v66, v48
	v_mov_b32_e32 v67, v52
	v_mov_b32_e32 v48, v53
	v_mov_b32_e32 v52, v49
	v_mov_b32_e32 v68, v54
	v_mov_b32_e32 v69, v50
	v_mov_b32_e32 v70, v50
	v_mov_b32_e32 v71, v54
	v_mov_b32_e32 v50, v55
	v_mov_b32_e32 v54, v51
	v_add_u32_e32 v72, 0x90, v154
	v_and_b32_e32 v73, 0xfdf, v72
	v_cmp_gt_i32_e32 vcc, s49, v72
	s_waitcnt vmcnt(2)
	v_pk_mul_f32 v[64:65], v[64:65], v[208:209]
	v_pk_mul_f32 v[56:57], v[66:67], v[208:209]
	v_pk_mul_f32 v[48:49], v[48:49], v[210:211]
	v_pk_mul_f32 v[52:53], v[52:53], v[210:211]
	v_pk_mul_f32 v[58:59], v[68:69], v[212:213]
	v_pk_mul_f32 v[50:51], v[50:51], v[214:215]
	v_pk_mul_f32 v[54:55], v[54:55], v[214:215]
	v_add_f32_e32 v56, v57, v56
	v_sub_f32_e32 v48, v48, v49
	v_add_f32_e32 v49, v53, v52
	v_sub_f32_e32 v52, v58, v59
	v_cndmask_b32_e32 v73, v164, v73, vcc
	v_pk_mul_f32 v[60:61], v[70:71], v[212:213]
	v_sub_f32_e32 v62, v64, v65
	v_sub_f32_e32 v50, v50, v51
	v_add_f32_e32 v51, v55, v54
	v_mul_f32_e32 v55, v151, v56
	v_mul_f32_e32 v48, v151, v48
	v_mul_f32_e32 v56, v151, v49
	v_mul_f32_e32 v49, v151, v52
	v_lshlrev_b32_e32 v132, 10, v73
	v_add_f32_e32 v53, v61, v60
	v_mul_f32_e32 v54, v151, v62
	v_mul_f32_e32 v50, v151, v50
	v_cvt_pk_bf16_f32 v48, v54, v48
	v_cvt_pk_bf16_f32 v49, v49, v50
	v_lshl_add_u64 v[74:75], v[138:139], 0, v[132:133]
	global_load_dwordx4 v[200:203], v[74:75], off
	global_load_dwordx4 v[204:207], v[74:75], off offset:16
	v_mul_f32_e32 v52, v151, v53
	v_mul_f32_e32 v51, v151, v51
	global_store_dwordx2 v[80:81], v[48:49], off offset:32
	v_cvt_pk_bf16_f32 v48, v55, v56
	v_cvt_pk_bf16_f32 v49, v52, v51
	global_store_dwordx2 v[80:81], v[48:49], off offset:288
	v_mov_b32_e32 v56, v44
	v_mov_b32_e32 v57, v40
	v_mov_b32_e32 v58, v40
	v_mov_b32_e32 v59, v44
	v_mov_b32_e32 v40, v45
	v_mov_b32_e32 v44, v41
	v_mov_b32_e32 v60, v46
	v_mov_b32_e32 v61, v42
	v_mov_b32_e32 v62, v42
	v_mov_b32_e32 v63, v46
	v_mov_b32_e32 v42, v47
	v_mov_b32_e32 v46, v43
	v_ashrrev_i32_e32 v73, 31, v72
	v_lshlrev_b64 v[64:65], 11, v[72:73]
	v_lshl_add_u64 v[64:65], s[0:1], 0, v[64:65]
	v_lshl_add_u64 v[64:65], v[64:65], 0, v[152:153]
	v_lshl_add_u64 v[66:67], v[140:141], 0, v[132:133]
	s_waitcnt vmcnt(2)
	global_load_dwordx4 v[208:211], v[66:67], off
	global_load_dwordx4 v[212:215], v[66:67], off offset:16
	v_pk_mul_f32 v[56:57], v[56:57], v[200:201]
	v_pk_mul_f32 v[48:49], v[58:59], v[200:201]
	v_pk_mul_f32 v[40:41], v[40:41], v[202:203]
	v_pk_mul_f32 v[44:45], v[44:45], v[202:203]
	v_pk_mul_f32 v[50:51], v[60:61], v[204:205]
	v_pk_mul_f32 v[42:43], v[42:43], v[206:207]
	v_pk_mul_f32 v[46:47], v[46:47], v[206:207]
	v_add_f32_e32 v48, v49, v48
	v_sub_f32_e32 v40, v40, v41
	v_add_f32_e32 v41, v45, v44
	v_sub_f32_e32 v44, v50, v51
	v_pk_mul_f32 v[52:53], v[62:63], v[204:205]
	v_sub_f32_e32 v54, v56, v57
	v_sub_f32_e32 v42, v42, v43
	v_add_f32_e32 v43, v47, v46
	v_mul_f32_e32 v47, v151, v48
	v_mul_f32_e32 v40, v151, v40
	v_mul_f32_e32 v48, v151, v41
	v_mul_f32_e32 v41, v151, v44
	v_add_f32_e32 v45, v53, v52
	v_mul_f32_e32 v46, v151, v54
	v_mul_f32_e32 v42, v151, v42
	v_cvt_pk_bf16_f32 v40, v46, v40
	v_cvt_pk_bf16_f32 v41, v41, v42
	v_mul_f32_e32 v44, v151, v45
	v_mul_f32_e32 v43, v151, v43
	global_store_dwordx2 v[64:65], v[40:41], off
	v_cvt_pk_bf16_f32 v40, v47, v48
	v_cvt_pk_bf16_f32 v41, v44, v43
	global_store_dwordx2 v[64:65], v[40:41], off offset:256
	v_mov_b32_e32 v48, v36
	v_mov_b32_e32 v49, v32
	v_mov_b32_e32 v50, v32
	v_mov_b32_e32 v51, v36
	v_mov_b32_e32 v32, v37
	v_mov_b32_e32 v36, v33
	v_mov_b32_e32 v52, v38
	v_mov_b32_e32 v53, v34
	v_mov_b32_e32 v54, v34
	v_mov_b32_e32 v55, v38
	v_mov_b32_e32 v34, v39
	v_mov_b32_e32 v38, v35
	v_add_u32_e32 v56, 0xa0, v154
	v_and_b32_e32 v57, 0xfef, v56
	v_cmp_gt_i32_e32 vcc, s49, v56
	s_waitcnt vmcnt(2)
	v_pk_mul_f32 v[48:49], v[48:49], v[208:209]
	v_pk_mul_f32 v[40:41], v[50:51], v[208:209]
	v_pk_mul_f32 v[32:33], v[32:33], v[210:211]
	v_pk_mul_f32 v[36:37], v[36:37], v[210:211]
	v_pk_mul_f32 v[42:43], v[52:53], v[212:213]
	v_pk_mul_f32 v[34:35], v[34:35], v[214:215]
	v_pk_mul_f32 v[38:39], v[38:39], v[214:215]
	v_add_f32_e32 v40, v41, v40
	v_sub_f32_e32 v32, v32, v33
	v_add_f32_e32 v33, v37, v36
	v_sub_f32_e32 v36, v42, v43
	v_cndmask_b32_e32 v57, v164, v57, vcc
	v_pk_mul_f32 v[44:45], v[54:55], v[212:213]
	v_sub_f32_e32 v46, v48, v49
	v_sub_f32_e32 v34, v34, v35
	v_add_f32_e32 v35, v39, v38
	v_mul_f32_e32 v39, v151, v40
	v_mul_f32_e32 v32, v151, v32
	v_mul_f32_e32 v40, v151, v33
	v_mul_f32_e32 v33, v151, v36
	v_lshlrev_b32_e32 v132, 10, v57
	v_add_f32_e32 v37, v45, v44
	v_mul_f32_e32 v38, v151, v46
	v_mul_f32_e32 v34, v151, v34
	v_cvt_pk_bf16_f32 v32, v38, v32
	v_cvt_pk_bf16_f32 v33, v33, v34
	v_lshl_add_u64 v[58:59], v[138:139], 0, v[132:133]
	global_load_dwordx4 v[200:203], v[58:59], off
	global_load_dwordx4 v[204:207], v[58:59], off offset:16
	v_mul_f32_e32 v36, v151, v37
	v_mul_f32_e32 v35, v151, v35
	global_store_dwordx2 v[64:65], v[32:33], off offset:32
	v_cvt_pk_bf16_f32 v32, v39, v40
	v_cvt_pk_bf16_f32 v33, v36, v35
	global_store_dwordx2 v[64:65], v[32:33], off offset:288
	v_mov_b32_e32 v40, v28
	v_mov_b32_e32 v41, v24
	v_mov_b32_e32 v42, v24
	v_mov_b32_e32 v43, v28
	v_mov_b32_e32 v24, v29
	v_mov_b32_e32 v28, v25
	v_mov_b32_e32 v44, v30
	v_mov_b32_e32 v45, v26
	v_mov_b32_e32 v46, v26
	v_mov_b32_e32 v47, v30
	v_mov_b32_e32 v26, v31
	v_mov_b32_e32 v30, v27
	v_ashrrev_i32_e32 v57, 31, v56
	v_lshlrev_b64 v[48:49], 11, v[56:57]
	v_lshl_add_u64 v[48:49], s[0:1], 0, v[48:49]
	v_lshl_add_u64 v[48:49], v[48:49], 0, v[152:153]
	v_lshl_add_u64 v[50:51], v[140:141], 0, v[132:133]
	s_waitcnt vmcnt(2)
	global_load_dwordx4 v[208:211], v[50:51], off
	global_load_dwordx4 v[212:215], v[50:51], off offset:16
	v_pk_mul_f32 v[40:41], v[40:41], v[200:201]
	v_pk_mul_f32 v[32:33], v[42:43], v[200:201]
	v_pk_mul_f32 v[24:25], v[24:25], v[202:203]
	v_pk_mul_f32 v[28:29], v[28:29], v[202:203]
	v_pk_mul_f32 v[34:35], v[44:45], v[204:205]
	v_pk_mul_f32 v[26:27], v[26:27], v[206:207]
	v_pk_mul_f32 v[30:31], v[30:31], v[206:207]
	v_add_f32_e32 v32, v33, v32
	v_sub_f32_e32 v24, v24, v25
	v_add_f32_e32 v25, v29, v28
	v_sub_f32_e32 v28, v34, v35
	v_pk_mul_f32 v[36:37], v[46:47], v[204:205]
	v_sub_f32_e32 v38, v40, v41
	v_sub_f32_e32 v26, v26, v27
	v_add_f32_e32 v27, v31, v30
	v_mul_f32_e32 v31, v151, v32
	v_mul_f32_e32 v24, v151, v24
	v_mul_f32_e32 v32, v151, v25
	v_mul_f32_e32 v25, v151, v28
	v_add_f32_e32 v29, v37, v36
	v_mul_f32_e32 v30, v151, v38
	v_mul_f32_e32 v26, v151, v26
	v_cvt_pk_bf16_f32 v24, v30, v24
	v_cvt_pk_bf16_f32 v25, v25, v26
	v_mul_f32_e32 v28, v151, v29
	v_mul_f32_e32 v27, v151, v27
	global_store_dwordx2 v[48:49], v[24:25], off
	v_cvt_pk_bf16_f32 v24, v31, v32
	v_cvt_pk_bf16_f32 v25, v28, v27
	global_store_dwordx2 v[48:49], v[24:25], off offset:256
	v_mov_b32_e32 v32, v20
	v_mov_b32_e32 v33, v16
	v_mov_b32_e32 v34, v16
	v_mov_b32_e32 v35, v20
	v_mov_b32_e32 v16, v21
	v_mov_b32_e32 v20, v17
	v_mov_b32_e32 v36, v22
	v_mov_b32_e32 v37, v18
	v_mov_b32_e32 v38, v18
	v_mov_b32_e32 v39, v22
	v_mov_b32_e32 v18, v23
	v_mov_b32_e32 v22, v19
	v_add_u32_e32 v40, 0xb0, v154
	v_and_b32_e32 v41, 0xfff, v40
	v_cmp_gt_i32_e32 vcc, s49, v40
	s_waitcnt vmcnt(2)
	v_pk_mul_f32 v[32:33], v[32:33], v[208:209]
	v_pk_mul_f32 v[24:25], v[34:35], v[208:209]
	v_pk_mul_f32 v[16:17], v[16:17], v[210:211]
	v_pk_mul_f32 v[20:21], v[20:21], v[210:211]
	v_pk_mul_f32 v[26:27], v[36:37], v[212:213]
	v_pk_mul_f32 v[18:19], v[18:19], v[214:215]
	v_pk_mul_f32 v[22:23], v[22:23], v[214:215]
	v_add_f32_e32 v24, v25, v24
	v_sub_f32_e32 v16, v16, v17
	v_add_f32_e32 v17, v21, v20
	v_sub_f32_e32 v20, v26, v27
	v_cndmask_b32_e32 v41, v164, v41, vcc
	v_pk_mul_f32 v[28:29], v[38:39], v[212:213]
	v_sub_f32_e32 v30, v32, v33
	v_sub_f32_e32 v18, v18, v19
	v_add_f32_e32 v19, v23, v22
	v_mul_f32_e32 v23, v151, v24
	v_mul_f32_e32 v16, v151, v16
	v_mul_f32_e32 v24, v151, v17
	v_mul_f32_e32 v17, v151, v20
	v_lshlrev_b32_e32 v132, 10, v41
	v_add_f32_e32 v21, v29, v28
	v_mul_f32_e32 v22, v151, v30
	v_mul_f32_e32 v18, v151, v18
	v_cvt_pk_bf16_f32 v16, v22, v16
	v_cvt_pk_bf16_f32 v17, v17, v18
	v_lshl_add_u64 v[42:43], v[138:139], 0, v[132:133]
	global_load_dwordx4 v[200:203], v[42:43], off
	global_load_dwordx4 v[204:207], v[42:43], off offset:16
	v_mul_f32_e32 v20, v151, v21
	v_mul_f32_e32 v19, v151, v19
	global_store_dwordx2 v[48:49], v[16:17], off offset:32
	v_cvt_pk_bf16_f32 v16, v23, v24
	v_cvt_pk_bf16_f32 v17, v20, v19
	global_store_dwordx2 v[48:49], v[16:17], off offset:288
	v_mov_b32_e32 v24, v12
	v_mov_b32_e32 v25, v8
	v_mov_b32_e32 v26, v8
	v_mov_b32_e32 v27, v12
	v_mov_b32_e32 v8, v13
	v_mov_b32_e32 v12, v9
	v_mov_b32_e32 v28, v14
	v_mov_b32_e32 v29, v10
	v_mov_b32_e32 v30, v10
	v_mov_b32_e32 v31, v14
	v_mov_b32_e32 v10, v15
	v_mov_b32_e32 v14, v11
	v_ashrrev_i32_e32 v41, 31, v40
	v_lshlrev_b64 v[32:33], 11, v[40:41]
	v_lshl_add_u64 v[32:33], s[0:1], 0, v[32:33]
	v_lshl_add_u64 v[32:33], v[32:33], 0, v[152:153]
	v_lshl_add_u64 v[34:35], v[140:141], 0, v[132:133]
	s_waitcnt vmcnt(2)
	global_load_dwordx4 v[208:211], v[34:35], off
	global_load_dwordx4 v[212:215], v[34:35], off offset:16
	v_pk_mul_f32 v[24:25], v[24:25], v[200:201]
	v_pk_mul_f32 v[16:17], v[26:27], v[200:201]
	v_pk_mul_f32 v[8:9], v[8:9], v[202:203]
	v_pk_mul_f32 v[12:13], v[12:13], v[202:203]
	v_pk_mul_f32 v[18:19], v[28:29], v[204:205]
	v_pk_mul_f32 v[10:11], v[10:11], v[206:207]
	v_pk_mul_f32 v[14:15], v[14:15], v[206:207]
	v_add_f32_e32 v16, v17, v16
	v_sub_f32_e32 v8, v8, v9
	v_add_f32_e32 v9, v13, v12
	v_sub_f32_e32 v12, v18, v19
	v_pk_mul_f32 v[20:21], v[30:31], v[204:205]
	v_sub_f32_e32 v22, v24, v25
	v_sub_f32_e32 v10, v10, v11
	v_add_f32_e32 v11, v15, v14
	v_mul_f32_e32 v15, v151, v16
	v_mul_f32_e32 v8, v151, v8
	v_mul_f32_e32 v16, v151, v9
	v_mul_f32_e32 v9, v151, v12
	v_add_f32_e32 v13, v21, v20
	v_mul_f32_e32 v14, v151, v22
	v_mul_f32_e32 v10, v151, v10
	v_cvt_pk_bf16_f32 v8, v14, v8
	v_cvt_pk_bf16_f32 v9, v9, v10
	v_mul_f32_e32 v12, v151, v13
	v_mul_f32_e32 v11, v151, v11
	global_store_dwordx2 v[32:33], v[8:9], off
	v_cvt_pk_bf16_f32 v8, v15, v16
	v_cvt_pk_bf16_f32 v9, v12, v11
	global_store_dwordx2 v[32:33], v[8:9], off offset:256
	v_mov_b32_e32 v16, v4
	v_mov_b32_e32 v17, v0
	v_mov_b32_e32 v18, v0
	v_mov_b32_e32 v19, v4
	v_mov_b32_e32 v0, v5
	v_mov_b32_e32 v4, v1
	v_mov_b32_e32 v20, v6
	v_mov_b32_e32 v21, v2
	v_mov_b32_e32 v22, v2
	v_mov_b32_e32 v23, v6
	v_mov_b32_e32 v2, v7
	v_mov_b32_e32 v6, v3
	s_waitcnt vmcnt(2)
	v_pk_mul_f32 v[16:17], v[16:17], v[208:209]
	v_pk_mul_f32 v[8:9], v[18:19], v[208:209]
	v_pk_mul_f32 v[0:1], v[0:1], v[210:211]
	v_pk_mul_f32 v[4:5], v[4:5], v[210:211]
	v_pk_mul_f32 v[10:11], v[20:21], v[212:213]
	v_pk_mul_f32 v[2:3], v[2:3], v[214:215]
	v_pk_mul_f32 v[6:7], v[6:7], v[214:215]
	v_add_f32_e32 v8, v9, v8
	v_sub_f32_e32 v0, v0, v1
	v_add_f32_e32 v1, v5, v4
	v_sub_f32_e32 v4, v10, v11
	v_pk_mul_f32 v[12:13], v[22:23], v[212:213]
	v_sub_f32_e32 v14, v16, v17
	v_sub_f32_e32 v2, v2, v3
	v_add_f32_e32 v3, v7, v6
	v_mul_f32_e32 v7, v151, v8
	v_mul_f32_e32 v0, v151, v0
	v_mul_f32_e32 v8, v151, v1
	v_mul_f32_e32 v1, v151, v4
	v_add_f32_e32 v5, v13, v12
	v_mul_f32_e32 v6, v151, v14
	v_mul_f32_e32 v2, v151, v2
	v_cvt_pk_bf16_f32 v0, v6, v0
	v_cvt_pk_bf16_f32 v1, v1, v2
	v_mul_f32_e32 v4, v151, v5
	v_mul_f32_e32 v3, v151, v3
	global_store_dwordx2 v[32:33], v[0:1], off offset:32
	v_cvt_pk_bf16_f32 v0, v7, v8
	v_cvt_pk_bf16_f32 v1, v4, v3
	global_store_dwordx2 v[32:33], v[0:1], off offset:288
	s_branch .LBB0_1002
